# SWA q prefetch (v58) plus 96 bytes of unreachable padding so the merge K-loop keeps v54's code placement (mod 256)
# speedup vs baseline: 1.0063x; 1.0063x over previous
; DI float bflo(unsigned w) { return __uint_as_float(w << 16); }
; DI float bfhi(unsigned w) { return __uint_as_float(w & 0xffff0000u); }
; DI void moba_combine_token(bf16_t* act, const unsigned* sel, const float* ml, int tok, int lane) {
;     const int hh = lane >> 3, ch = lane & 7;
;     const int b = tok >> 13, qpos = tok & (SEQ - 1);
;     bf16_t* rowp = act + (size_t)tok * PITCH;
;     const unsigned word = sel[(size_t)(b * 8 + hh) * SEQ + qpos];
;     const f32x4* mlp = (const f32x4*)(ml + ((size_t)tok * 8 + hh) * 8);
;     const f32x4 a = mlp[0], c = mlp[1];
;     const u32x4 v3 = *(const u32x4*)(rowp + C_KC + hh * 64 + ch * 8);
;     u32x4 vs[3];
; #pragma unroll
;     for (int s = 0; s < 3; ++s) vs[s] = *(const u32x4*)(rowp + C_KA + (s * 8 + hh) * 64 + ch * 8);
;     const u32x4 g = *(const u32x4*)(rowp + C_GB + hh * 64 + ch * 8);
;     const int ns = __popc(word);
;     const float m0 = ns > 0 ? a.x : NEG_INF, m1 = ns > 1 ? a.z : NEG_INF, m2 = ns > 2 ? c.x : NEG_INF, m3 = c.z;
;     const float M = fmaxf(fmaxf(m0, m1), fmaxf(m2, m3));
;     const float w0 = ns > 0 ? a.y * fast_exp2(m0 - M) : 0.f, w1 = ns > 1 ? a.w * fast_exp2(m1 - M) : 0.f, w2 = ns > 2 ? c.y * fast_exp2(m2 - M) : 0.f, w3 = c.w * fast_exp2(m3 - M);
;     const float inv = fast_rcp((w0 + w1) + (w2 + w3));
;     float acc[8];
;     acc[0] = w3 * bflo(v3.x); acc[1] = w3 * bfhi(v3.x); acc[2] = w3 * bflo(v3.y); acc[3] = w3 * bfhi(v3.y); acc[4] = w3 * bflo(v3.z); acc[5] = w3 * bfhi(v3.z); acc[6] = w3 * bflo(v3.w); acc[7] = w3 * bfhi(v3.w);
; #pragma unroll
;     for (int s = 0; s < 3; ++s) {
;         const float w = s == 0 ? w0 : (s == 1 ? w1 : w2);
;         const bool use = s < ns;
;         u32x4 v = vs[s]; if (!use) v = (u32x4){0u, 0u, 0u, 0u};
;         acc[0] += w * bflo(v.x); acc[1] += w * bfhi(v.x); acc[2] += w * bflo(v.y); acc[3] += w * bfhi(v.y); acc[4] += w * bflo(v.z); acc[5] += w * bfhi(v.z); acc[6] += w * bflo(v.w); acc[7] += w * bfhi(v.w);
; __global__ void __launch_bounds__(512, 2) hybrid_fwd(Params p) {
;     ...
;             for (int tok = gw; tok < T; tok += 2 * NGW) {
;                 moba_combine_token(act, (const unsigned*)(ws + WS_SEL), (const float*)(ws + WS_ML), tok, lane);
;                 if (tok + NGW < T) moba_combine_token(act, (const unsigned*)(ws + WS_SEL), (const float*)(ws + WS_ML), tok + NGW, lane);
.LBB0_583:
	s_and_b32 s14, s8, 0x1fff
	s_ashr_i32 s9, s8, 31
	s_mul_i32 s12, s8, 0x3200
	s_mul_hi_i32 s13, s8, 0x3200
	s_add_u32 s12, s10, s12
	s_addc_u32 s13, s11, s13
	s_ashr_i32 s15, s8, 10
	v_and_or_b32 v2, s15, -8, v13
	v_ashrrev_i32_e32 v3, 31, v2
	v_lshlrev_b64 v[2:3], 15, v[2:3]
	v_lshl_add_u64 v[2:3], s[6:7], 0, v[2:3]
	s_lshl_b32 s38, s14, 2
	v_lshl_add_u64 v[2:3], v[2:3], 0, s[38:39]
	global_load_dword v22, v[2:3], off
	s_lshl_b64 s[14:15], s[8:9], 8
	v_lshl_add_u64 v[2:3], v[10:11], 0, s[14:15]
	global_load_dwordx4 v[28:31], v[2:3], off offset:16
	global_load_dwordx4 v[18:21], v[2:3], off
	v_lshlrev_b32_e32 v0, 1, v12
	v_mov_b32_e32 v15, v1
	v_lshl_add_u64 v[2:3], s[12:13], 0, v[0:1]
	v_lshl_add_u64 v[2:3], v[2:3], 0, v[14:15]
	v_add_co_u32_e32 v4, vcc, s23, v2
	s_add_i32 s8, s8, s91
	s_nop 0
	v_addc_co_u32_e32 v5, vcc, 0, v3, vcc
	global_load_dwordx4 v[6:9], v[4:5], off offset:1024
	v_lshl_add_u64 v[4:5], s[12:13], 0, v[14:15]
	v_lshl_add_u64 v[4:5], v[4:5], 0, v[0:1]
	global_load_dwordx4 v[32:35], v[4:5], off offset:1024
	global_load_dwordx4 v[36:39], v[4:5], off offset:2048
	global_load_dwordx4 v[40:43], v[4:5], off offset:3072
	v_add_co_u32_e32 v16, vcc, s34, v2
	s_cmpk_gt_i32 s8, 0x7fff
	s_nop 0
	v_addc_co_u32_e32 v17, vcc, 0, v3, vcc
	global_load_dwordx4 v[2:5], v[16:17], off offset:3072
	s_waitcnt vmcnt(7)
	v_bcnt_u32_b32 v23, v22, 0
	v_cmp_lt_u32_e32 vcc, 2, v23
	v_cmp_eq_u32_e64 s[42:43], 0, v22
	v_cmp_lt_u32_e64 s[40:41], 1, v23
	s_waitcnt vmcnt(6)
	v_cndmask_b32_e32 v22, v235, v28, vcc
	v_max_f32_e32 v23, v22, v22
	v_max_f32_e32 v24, v30, v30
	s_waitcnt vmcnt(5)
	v_cndmask_b32_e64 v18, v18, v235, s[42:43]
	v_cndmask_b32_e64 v20, v235, v20, s[40:41]
	v_max_f32_e32 v23, v23, v24
	v_max3_f32 v23, v18, v20, v23
	v_sub_f32_e32 v18, v18, v23
	v_exp_f32_e32 v18, v18
	s_waitcnt vmcnt(3)
	v_cndmask_b32_e64 v28, v34, 0, s[42:43]
	v_cndmask_b32_e64 v44, v33, 0, s[42:43]
	v_mul_f32_e32 v18, v19, v18
	v_cndmask_b32_e64 v24, v18, 0, s[42:43]
	v_sub_f32_e32 v18, v20, v23
	v_exp_f32_e32 v18, v18
	s_waitcnt vmcnt(1)
	v_cndmask_b32_e32 v25, 0, v42, vcc
	v_cndmask_b32_e64 v27, 0, v38, s[40:41]
	v_cndmask_b32_e64 v36, 0, v36, s[40:41]
	v_mul_f32_e32 v18, v21, v18
	v_cndmask_b32_e64 v20, 0, v18, s[40:41]
	v_sub_f32_e32 v18, v22, v23
	v_exp_f32_e32 v18, v18
	v_and_b32_e32 v33, 0xffff0000, v6
	v_cndmask_b32_e64 v21, 0, v39, s[40:41]
	v_cndmask_b32_e32 v19, 0, v43, vcc
	v_mul_f32_e32 v18, v29, v18
	v_cndmask_b32_e32 v22, 0, v18, vcc
	v_sub_f32_e32 v18, v30, v23
	v_exp_f32_e32 v18, v18
	v_cndmask_b32_e64 v23, v35, 0, s[42:43]
	v_cndmask_b32_e64 v35, v32, 0, s[42:43]
	v_add_f32_e32 v32, v24, v20
	v_mul_f32_e32 v26, v31, v18
	v_fma_f32 v18, v31, v18, v22
	v_lshlrev_b32_e32 v34, 16, v35
	v_and_b32_e32 v35, 0xffff0000, v35
	v_add_f32_e32 v18, v32, v18
	v_lshlrev_b32_e32 v32, 16, v6
	v_pk_mul_f32 v[34:35], v[24:25], v[34:35] op_sel_hi:[0,1]
	v_cndmask_b32_e64 v30, 0, v37, s[40:41]
	v_cndmask_b32_e32 v37, 0, v40, vcc
	v_pk_fma_f32 v[32:33], v[26:27], v[32:33], v[34:35] op_sel_hi:[0,1,1]
	v_lshlrev_b32_e32 v34, 16, v36
	v_and_b32_e32 v35, 0xffff0000, v36
	v_pk_fma_f32 v[32:33], v[20:21], v[34:35], v[32:33] op_sel_hi:[0,1,1]
	v_lshlrev_b32_e32 v34, 16, v37
	v_and_b32_e32 v35, 0xffff0000, v37
	v_pk_fma_f32 v[32:33], v[22:23], v[34:35], v[32:33] op_sel_hi:[0,1,1]
	s_waitcnt vmcnt(0)
	v_lshlrev_b32_e32 v34, 16, v2
	v_and_b32_e32 v35, 0xffff0000, v2
	v_mul_f32_e32 v2, 0xbfb8aa3b, v34
	v_exp_f32_e32 v2, v2
	v_rcp_f32_e32 v18, v18
	v_lshlrev_b32_e32 v6, 16, v7
	v_and_b32_e32 v7, 0xffff0000, v7
	v_add_f32_e32 v2, 1.0, v2
	v_rcp_f32_e32 v36, v2
	v_mul_f32_e32 v2, 0xbfb8aa3b, v35
	v_exp_f32_e32 v2, v2
	v_pk_mul_f32 v[32:33], v[18:19], v[32:33] op_sel_hi:[0,1]
	v_cndmask_b32_e32 v29, 0, v41, vcc
	v_and_b32_e32 v31, 0xffff0000, v29
	v_add_f32_e32 v2, 1.0, v2
	v_rcp_f32_e32 v37, v2
	s_nop 0
	v_pk_mul_f32 v[34:35], v[36:37], v[34:35]
	s_nop 0
	v_pk_mul_f32 v[32:33], v[34:35], v[32:33]
	s_nop 0
	v_cvt_pk_bf16_f32 v2, v32, v33
	v_lshlrev_b32_e32 v32, 16, v44
	v_and_b32_e32 v33, 0xffff0000, v44
	v_pk_mul_f32 v[32:33], v[24:25], v[32:33] op_sel_hi:[0,1]
	v_pk_fma_f32 v[6:7], v[26:27], v[6:7], v[32:33] op_sel_hi:[0,1,1]
	v_lshlrev_b32_e32 v32, 16, v30
	v_and_b32_e32 v33, 0xffff0000, v30
	v_pk_fma_f32 v[6:7], v[20:21], v[32:33], v[6:7] op_sel_hi:[0,1,1]
	v_lshlrev_b32_e32 v30, 16, v29
	v_pk_fma_f32 v[6:7], v[22:23], v[30:31], v[6:7] op_sel_hi:[0,1,1]
	v_lshlrev_b32_e32 v30, 16, v3
	v_and_b32_e32 v31, 0xffff0000, v3
	v_mul_f32_e32 v3, 0xbfb8aa3b, v30
	v_exp_f32_e32 v3, v3
	v_pk_mul_f32 v[6:7], v[18:19], v[6:7] op_sel_hi:[0,1]
	v_add_f32_e32 v3, 1.0, v3
	v_rcp_f32_e32 v32, v3
	v_mul_f32_e32 v3, 0xbfb8aa3b, v31
	v_exp_f32_e32 v3, v3
	s_nop 0
	v_add_f32_e32 v3, 1.0, v3
	v_rcp_f32_e32 v33, v3
	s_nop 0
	v_pk_mul_f32 v[30:31], v[32:33], v[30:31]
	s_nop 0
	v_pk_mul_f32 v[6:7], v[30:31], v[6:7]
	v_lshlrev_b32_e32 v30, 16, v28
	v_and_b32_e32 v31, 0xffff0000, v28
	v_cvt_pk_bf16_f32 v3, v6, v7
	v_lshlrev_b32_e32 v6, 16, v8
	v_and_b32_e32 v7, 0xffff0000, v8
	v_pk_mul_f32 v[28:29], v[24:25], v[30:31] op_sel_hi:[0,1]
	v_pk_fma_f32 v[6:7], v[26:27], v[6:7], v[28:29] op_sel_hi:[0,1,1]
	v_lshlrev_b32_e32 v28, 16, v27
	v_and_b32_e32 v29, 0xffff0000, v27
	v_pk_fma_f32 v[6:7], v[20:21], v[28:29], v[6:7] op_sel_hi:[0,1,1]
	v_lshlrev_b32_e32 v28, 16, v25
	v_and_b32_e32 v29, 0xffff0000, v25
	v_pk_fma_f32 v[6:7], v[22:23], v[28:29], v[6:7] op_sel_hi:[0,1,1]
	v_lshlrev_b32_e32 v28, 16, v4
	v_and_b32_e32 v29, 0xffff0000, v4
	v_mul_f32_e32 v4, 0xbfb8aa3b, v28
	v_exp_f32_e32 v4, v4
	v_pk_mul_f32 v[6:7], v[18:19], v[6:7] op_sel_hi:[0,1]
	v_lshlrev_b32_e32 v8, 16, v23
	v_add_f32_e32 v4, 1.0, v4
	v_rcp_f32_e32 v30, v4
	v_mul_f32_e32 v4, 0xbfb8aa3b, v29
	v_exp_f32_e32 v4, v4
	s_nop 0
	v_add_f32_e32 v4, 1.0, v4
	v_rcp_f32_e32 v31, v4
	s_nop 0
	v_pk_mul_f32 v[28:29], v[30:31], v[28:29]
	s_nop 0
	v_pk_mul_f32 v[6:7], v[28:29], v[6:7]
	s_nop 0
	v_cvt_pk_bf16_f32 v4, v6, v7
	v_lshlrev_b32_e32 v6, 16, v9
	v_and_b32_e32 v7, 0xffff0000, v9
	v_and_b32_e32 v9, 0xffff0000, v23
	v_pk_mul_f32 v[8:9], v[24:25], v[8:9] op_sel_hi:[0,1]
	v_pk_fma_f32 v[6:7], v[26:27], v[6:7], v[8:9] op_sel_hi:[0,1,1]
	v_lshlrev_b32_e32 v8, 16, v21
	v_and_b32_e32 v9, 0xffff0000, v21
	v_pk_fma_f32 v[6:7], v[20:21], v[8:9], v[6:7] op_sel_hi:[0,1,1]
	v_lshlrev_b32_e32 v8, 16, v19
	v_and_b32_e32 v9, 0xffff0000, v19
	v_pk_fma_f32 v[6:7], v[22:23], v[8:9], v[6:7] op_sel_hi:[0,1,1]
	v_lshlrev_b32_e32 v8, 16, v5
	v_and_b32_e32 v9, 0xffff0000, v5
	v_mul_f32_e32 v5, 0xbfb8aa3b, v8
	v_exp_f32_e32 v5, v5
	v_pk_mul_f32 v[6:7], v[18:19], v[6:7] op_sel_hi:[0,1]
	v_add_f32_e32 v5, 1.0, v5
	v_rcp_f32_e32 v20, v5
	v_mul_f32_e32 v5, 0xbfb8aa3b, v9
	v_exp_f32_e32 v5, v5
	s_nop 0
	v_add_f32_e32 v5, 1.0, v5
	v_rcp_f32_e32 v21, v5
	s_nop 0
	v_pk_mul_f32 v[8:9], v[20:21], v[8:9]
	s_nop 0
	v_pk_mul_f32 v[6:7], v[8:9], v[6:7]
	s_nop 0
	v_cvt_pk_bf16_f32 v5, v6, v7
	global_store_dwordx4 v[16:17], v[2:5], off
	s_cbranch_scc1 .LBB0_582
; DI float bflo(unsigned w) { return __uint_as_float(w << 16); }
; DI float bfhi(unsigned w) { return __uint_as_float(w & 0xffff0000u); }
; DI void moba_combine_token(bf16_t* act, const unsigned* sel, const float* ml, int tok, int lane) {
;     const int hh = lane >> 3, ch = lane & 7;
;     const int b = tok >> 13, qpos = tok & (SEQ - 1);
;     bf16_t* rowp = act + (size_t)tok * PITCH;
;     const unsigned word = sel[(size_t)(b * 8 + hh) * SEQ + qpos];
;     const f32x4* mlp = (const f32x4*)(ml + ((size_t)tok * 8 + hh) * 8);
;     const f32x4 a = mlp[0], c = mlp[1];
;     const u32x4 v3 = *(const u32x4*)(rowp + C_KC + hh * 64 + ch * 8);
;     u32x4 vs[3];
; #pragma unroll
;     for (int s = 0; s < 3; ++s) vs[s] = *(const u32x4*)(rowp + C_KA + (s * 8 + hh) * 64 + ch * 8);
;     const u32x4 g = *(const u32x4*)(rowp + C_GB + hh * 64 + ch * 8);
;     const int ns = __popc(word);
;     const float m0 = ns > 0 ? a.x : NEG_INF, m1 = ns > 1 ? a.z : NEG_INF, m2 = ns > 2 ? c.x : NEG_INF, m3 = c.z;
;     const float M = fmaxf(fmaxf(m0, m1), fmaxf(m2, m3));
;     const float w0 = ns > 0 ? a.y * fast_exp2(m0 - M) : 0.f, w1 = ns > 1 ? a.w * fast_exp2(m1 - M) : 0.f, w2 = ns > 2 ? c.y * fast_exp2(m2 - M) : 0.f, w3 = c.w * fast_exp2(m3 - M);
;     const float inv = fast_rcp((w0 + w1) + (w2 + w3));
;     float acc[8];
;     acc[0] = w3 * bflo(v3.x); acc[1] = w3 * bfhi(v3.x); acc[2] = w3 * bflo(v3.y); acc[3] = w3 * bfhi(v3.y); acc[4] = w3 * bflo(v3.z); acc[5] = w3 * bfhi(v3.z); acc[6] = w3 * bflo(v3.w); acc[7] = w3 * bfhi(v3.w);
; #pragma unroll
;     for (int s = 0; s < 3; ++s) {
;         const float w = s == 0 ? w0 : (s == 1 ? w1 : w2);
;         const bool use = s < ns;
;         u32x4 v = vs[s]; if (!use) v = (u32x4){0u, 0u, 0u, 0u};
;         acc[0] += w * bflo(v.x); acc[1] += w * bfhi(v.x); acc[2] += w * bflo(v.y); acc[3] += w * bfhi(v.y); acc[4] += w * bflo(v.z); acc[5] += w * bfhi(v.z); acc[6] += w * bflo(v.w); acc[7] += w * bfhi(v.w);
;     }
;     u32x4 y;
;     y.x = cvtpk(acc[0] * inv * silu_(bflo(g.x)), acc[1] * inv * silu_(bfhi(g.x))); y.y = cvtpk(acc[2] * inv * silu_(bflo(g.y)), acc[3] * inv * silu_(bfhi(g.y)));
;     y.z = cvtpk(acc[4] * inv * silu_(bflo(g.z)), acc[5] * inv * silu_(bfhi(g.z))); y.w = cvtpk(acc[6] * inv * silu_(bflo(g.w)), acc[7] * inv * silu_(bfhi(g.w)));
;     *(u32x4*)(rowp + C_QB + hh * 64 + ch * 8) = y;
	s_and_b32 s14, s8, 0x1fff
	s_ashr_i32 s9, s8, 31
	s_mul_i32 s12, s8, 0x3200
	s_mul_hi_i32 s13, s8, 0x3200
	s_add_u32 s12, s10, s12
	s_addc_u32 s13, s11, s13
	s_ashr_i32 s15, s8, 10
	v_and_or_b32 v2, s15, -8, v13
	v_ashrrev_i32_e32 v3, 31, v2
	v_lshlrev_b64 v[2:3], 15, v[2:3]
	v_lshl_add_u64 v[2:3], s[6:7], 0, v[2:3]
	s_lshl_b32 s38, s14, 2
	v_lshl_add_u64 v[2:3], v[2:3], 0, s[38:39]
	global_load_dword v22, v[2:3], off
	s_lshl_b64 s[14:15], s[8:9], 8
	v_lshl_add_u64 v[2:3], v[10:11], 0, s[14:15]
	global_load_dwordx4 v[26:29], v[2:3], off offset:16
	global_load_dwordx4 v[18:21], v[2:3], off
	v_lshl_add_u64 v[2:3], s[12:13], 0, v[0:1]
	v_lshl_add_u64 v[2:3], v[2:3], 0, v[14:15]
	v_add_co_u32_e32 v4, vcc, s23, v2
	s_waitcnt vmcnt(2)
	v_cmp_eq_u32_e64 s[42:43], 0, v22
	v_addc_co_u32_e32 v5, vcc, 0, v3, vcc
	global_load_dwordx4 v[6:9], v[4:5], off offset:1024
	v_lshl_add_u64 v[4:5], s[12:13], 0, v[14:15]
	v_lshl_add_u64 v[4:5], v[4:5], 0, v[0:1]
	global_load_dwordx4 v[30:33], v[4:5], off offset:1024
	global_load_dwordx4 v[34:37], v[4:5], off offset:2048
	global_load_dwordx4 v[38:41], v[4:5], off offset:3072
	v_add_co_u32_e32 v16, vcc, s34, v2
	v_bcnt_u32_b32 v0, v22, 0
	s_nop 0
	v_addc_co_u32_e32 v17, vcc, 0, v3, vcc
	global_load_dwordx4 v[2:5], v[16:17], off offset:3072
	v_cmp_lt_u32_e32 vcc, 2, v0
	v_cmp_lt_u32_e64 s[40:41], 1, v0
	s_waitcnt vmcnt(5)
	v_cndmask_b32_e64 v15, v18, v235, s[42:43]
	v_cndmask_b32_e32 v0, v235, v26, vcc
	v_cndmask_b32_e64 v18, v235, v20, s[40:41]
	v_max_f32_e32 v20, v0, v0
	v_max_f32_e32 v22, v28, v28
	v_max_f32_e32 v20, v20, v22
	v_max3_f32 v23, v15, v18, v20
	v_sub_f32_e32 v15, v15, v23
	v_exp_f32_e32 v15, v15
	v_sub_f32_e32 v0, v0, v23
	v_exp_f32_e32 v0, v0
	v_mul_f32_e32 v15, v19, v15
	v_cndmask_b32_e64 v22, v15, 0, s[42:43]
	v_sub_f32_e32 v15, v18, v23
	v_exp_f32_e32 v15, v15
	v_mul_f32_e32 v0, v27, v0
	v_cndmask_b32_e32 v20, 0, v0, vcc
	v_sub_f32_e32 v0, v28, v23
	v_exp_f32_e32 v0, v0
	v_mul_f32_e32 v15, v21, v15
	v_cndmask_b32_e64 v18, 0, v15, s[40:41]
	v_mul_f32_e32 v24, v29, v0
	v_fma_f32 v0, v29, v0, v20
	s_waitcnt vmcnt(3)
	v_cndmask_b32_e64 v21, v33, 0, s[42:43]
	v_cndmask_b32_e64 v33, v30, 0, s[42:43]
	v_cndmask_b32_e64 v26, v32, 0, s[42:43]
	s_waitcnt vmcnt(1)
	v_cndmask_b32_e32 v23, 0, v40, vcc
	v_add_f32_e32 v30, v22, v18
	v_lshlrev_b32_e32 v32, 16, v33
	v_and_b32_e32 v33, 0xffff0000, v33
	v_cndmask_b32_e64 v42, v31, 0, s[42:43]
	v_cndmask_b32_e64 v25, 0, v36, s[40:41]
	v_cndmask_b32_e64 v34, 0, v34, s[40:41]
	v_add_f32_e32 v0, v30, v0
	v_lshlrev_b32_e32 v30, 16, v6
	v_and_b32_e32 v31, 0xffff0000, v6
	v_pk_mul_f32 v[32:33], v[22:23], v[32:33] op_sel_hi:[0,1]
	v_cndmask_b32_e64 v19, 0, v37, s[40:41]
	v_cndmask_b32_e64 v28, 0, v35, s[40:41]
	v_cndmask_b32_e32 v35, 0, v38, vcc
	v_pk_fma_f32 v[30:31], v[24:25], v[30:31], v[32:33] op_sel_hi:[0,1,1]
	v_lshlrev_b32_e32 v32, 16, v34
	v_and_b32_e32 v33, 0xffff0000, v34
	v_pk_fma_f32 v[30:31], v[18:19], v[32:33], v[30:31] op_sel_hi:[0,1,1]
	v_lshlrev_b32_e32 v32, 16, v35
	v_and_b32_e32 v33, 0xffff0000, v35
	v_pk_fma_f32 v[30:31], v[20:21], v[32:33], v[30:31] op_sel_hi:[0,1,1]
	s_waitcnt vmcnt(0)
	v_lshlrev_b32_e32 v32, 16, v2
	v_and_b32_e32 v33, 0xffff0000, v2
	v_mul_f32_e32 v2, 0xbfb8aa3b, v32
	v_exp_f32_e32 v2, v2
	v_rcp_f32_e32 v0, v0
	v_lshlrev_b32_e32 v6, 16, v7
	v_and_b32_e32 v7, 0xffff0000, v7
	v_add_f32_e32 v2, 1.0, v2
	v_rcp_f32_e32 v34, v2
	v_mul_f32_e32 v2, 0xbfb8aa3b, v33
	v_exp_f32_e32 v2, v2
	v_pk_mul_f32 v[30:31], v[0:1], v[30:31] op_sel_hi:[0,1]
	v_cndmask_b32_e32 v27, 0, v39, vcc
	v_and_b32_e32 v29, 0xffff0000, v27
	v_add_f32_e32 v2, 1.0, v2
	v_rcp_f32_e32 v35, v2
	v_cndmask_b32_e32 v15, 0, v41, vcc
	v_pk_mul_f32 v[32:33], v[34:35], v[32:33]
	s_nop 0
	v_pk_mul_f32 v[30:31], v[32:33], v[30:31]
	s_nop 0
	v_cvt_pk_bf16_f32 v2, v30, v31
	v_lshlrev_b32_e32 v30, 16, v42
	v_and_b32_e32 v31, 0xffff0000, v42
	v_pk_mul_f32 v[30:31], v[22:23], v[30:31] op_sel_hi:[0,1]
	v_pk_fma_f32 v[6:7], v[24:25], v[6:7], v[30:31] op_sel_hi:[0,1,1]
	v_lshlrev_b32_e32 v30, 16, v28
	v_and_b32_e32 v31, 0xffff0000, v28
	v_pk_fma_f32 v[6:7], v[18:19], v[30:31], v[6:7] op_sel_hi:[0,1,1]
	v_lshlrev_b32_e32 v28, 16, v27
	v_pk_fma_f32 v[6:7], v[20:21], v[28:29], v[6:7] op_sel_hi:[0,1,1]
	v_lshlrev_b32_e32 v28, 16, v3
	v_and_b32_e32 v29, 0xffff0000, v3
	v_mul_f32_e32 v3, 0xbfb8aa3b, v28
	v_exp_f32_e32 v3, v3
	v_pk_mul_f32 v[6:7], v[0:1], v[6:7] op_sel_hi:[0,1]
	v_add_f32_e32 v3, 1.0, v3
	v_rcp_f32_e32 v30, v3
	v_mul_f32_e32 v3, 0xbfb8aa3b, v29
	v_exp_f32_e32 v3, v3
	s_nop 0
	v_add_f32_e32 v3, 1.0, v3
	v_rcp_f32_e32 v31, v3
	s_nop 0
	v_pk_mul_f32 v[28:29], v[30:31], v[28:29]
	s_nop 0
	v_pk_mul_f32 v[6:7], v[28:29], v[6:7]
	v_lshlrev_b32_e32 v28, 16, v26
	v_and_b32_e32 v29, 0xffff0000, v26
	v_cvt_pk_bf16_f32 v3, v6, v7
	v_lshlrev_b32_e32 v6, 16, v8
	v_and_b32_e32 v7, 0xffff0000, v8
	v_pk_mul_f32 v[26:27], v[22:23], v[28:29] op_sel_hi:[0,1]
	v_pk_fma_f32 v[6:7], v[24:25], v[6:7], v[26:27] op_sel_hi:[0,1,1]
	v_lshlrev_b32_e32 v26, 16, v25
	v_and_b32_e32 v27, 0xffff0000, v25
	v_pk_fma_f32 v[6:7], v[18:19], v[26:27], v[6:7] op_sel_hi:[0,1,1]
	v_lshlrev_b32_e32 v26, 16, v23
	v_and_b32_e32 v27, 0xffff0000, v23
	v_pk_fma_f32 v[6:7], v[20:21], v[26:27], v[6:7] op_sel_hi:[0,1,1]
	v_lshlrev_b32_e32 v26, 16, v4
	v_and_b32_e32 v27, 0xffff0000, v4
	v_mul_f32_e32 v4, 0xbfb8aa3b, v26
	v_exp_f32_e32 v4, v4
	v_pk_mul_f32 v[6:7], v[0:1], v[6:7] op_sel_hi:[0,1]
	v_lshlrev_b32_e32 v8, 16, v21
	v_add_f32_e32 v4, 1.0, v4
	v_rcp_f32_e32 v28, v4
	v_mul_f32_e32 v4, 0xbfb8aa3b, v27
	v_exp_f32_e32 v4, v4
	s_nop 0
	v_add_f32_e32 v4, 1.0, v4
	v_rcp_f32_e32 v29, v4
	s_nop 0
	v_pk_mul_f32 v[26:27], v[28:29], v[26:27]
	s_nop 0
	v_pk_mul_f32 v[6:7], v[26:27], v[6:7]
	s_nop 0
	v_cvt_pk_bf16_f32 v4, v6, v7
	v_lshlrev_b32_e32 v6, 16, v9
	v_and_b32_e32 v7, 0xffff0000, v9
	v_and_b32_e32 v9, 0xffff0000, v21
	v_pk_mul_f32 v[8:9], v[22:23], v[8:9] op_sel_hi:[0,1]
	v_pk_fma_f32 v[6:7], v[24:25], v[6:7], v[8:9] op_sel_hi:[0,1,1]
	v_lshlrev_b32_e32 v8, 16, v19
	v_and_b32_e32 v9, 0xffff0000, v19
	v_pk_fma_f32 v[6:7], v[18:19], v[8:9], v[6:7] op_sel_hi:[0,1,1]
	v_lshlrev_b32_e32 v8, 16, v15
	v_and_b32_e32 v9, 0xffff0000, v15
	v_pk_fma_f32 v[6:7], v[20:21], v[8:9], v[6:7] op_sel_hi:[0,1,1]
	v_lshlrev_b32_e32 v8, 16, v5
	v_and_b32_e32 v9, 0xffff0000, v5
	v_mul_f32_e32 v5, 0xbfb8aa3b, v8
	v_pk_mul_f32 v[6:7], v[0:1], v[6:7] op_sel_hi:[0,1]
	v_mul_f32_e32 v0, 0xbfb8aa3b, v9
	v_exp_f32_e32 v5, v5
	v_exp_f32_e32 v0, v0
	v_add_f32_e32 v5, 1.0, v5
	v_add_f32_e32 v0, 1.0, v0
	v_rcp_f32_e32 v18, v5
	v_rcp_f32_e32 v19, v0
	s_nop 0
	v_pk_mul_f32 v[8:9], v[18:19], v[8:9]
	s_nop 0
	v_pk_mul_f32 v[6:7], v[8:9], v[6:7]
	s_nop 0
	v_cvt_pk_bf16_f32 v5, v6, v7
	global_store_dwordx4 v[16:17], v[2:5], off
	s_branch .LBB0_582
	s_nop 0
	s_nop 0
	s_nop 0
	s_nop 0
	s_nop 0
	s_nop 0
	s_nop 0
	s_nop 0
	s_nop 0
	s_nop 0
	s_nop 0
	s_nop 0
	s_nop 0
	s_nop 0
	s_nop 0
	s_nop 0
	s_nop 0
	s_nop 0
	s_nop 0
	s_nop 0
	s_nop 0
	s_nop 0
	s_nop 0
	s_nop 0
